# v11: + GEMM1 column-tile roles 2<->8, 3<->9 swapped so each CU's static tile set mixes cheap/silu/log epilogues evenly
# baseline (speedup 1.0000x reference)
;     DI bool next(int i, Unit& u) const {
;         const long L = (long)i * G + c; if (L >= nwg) return false;
;         int wgid = (int)L; { const int q = nwg / NXCD, r = nwg % NXCD, xcd = wgid % NXCD, off = wgid / NXCD; wgid = (xcd < r ? xcd * (q + 1) : r * (q + 1) + (xcd - r) * q) + off; }
;         const int nig = WGM * nN, gid = wgid / nig, fm = gid * WGM, gsz = (nM - fm) < WGM ? (nM - fm) : WGM;
;         u.pm = fm + ((wgid % nig) % gsz); u.pn = (wgid % nig) / gsz; return true;
;     }
.LBB0_383:
	s_movk_i32 s0, 0xc00
	s_ashr_i32 s2, s0, 31
	s_lshr_b32 s2, s2, 24
	s_add_i32 s0, s0, s2
	s_ashr_i32 s4, s0, 8
	s_movk_i32 s12, 0x400
	s_mov_b32 s8, s68
	v_readlane_b32 s18, v238, 0
	s_mul_i32 s46, s4, 0xc0
	v_mov_b32_e32 v12, v164
	s_cmp_lt_i32 s18, s46
	s_cselect_b64 s[2:3], -1, 0
	v_readfirstlane_b32 s19, v12
	s_cmp_ge_i32 s18, s46
	s_mul_i32 s36, s4, 24
	s_cbranch_scc1 .LBB0_385
	s_lshl_b32 s10, s4, 3
	s_ashr_i32 s11, s4, 31
	s_add_i32 s13, s10, s11
	s_xor_b32 s13, s13, s11
	v_cvt_f32_u32_e32 v0, s13
	s_ashr_i32 s0, s18, 31
	s_lshr_b32 s0, s0, 29
	s_add_i32 s0, s18, s0
	v_rcp_iflag_f32_e32 v0, v0
	s_ashr_i32 s5, s0, 3
	s_and_b32 s0, s0, -8
	s_sub_i32 s0, s18, s0
	v_mul_f32_e32 v0, 0x4f7ffffe, v0
	v_cvt_u32_f32_e32 v0, v0
	s_lshr_b32 s14, s0, 31
	s_or_b32 s14, s14, s36
	s_mul_i32 s0, s14, s0
	s_sub_i32 s14, 0, s13
	v_readfirstlane_b32 s15, v0
	s_add_i32 s0, s0, s5
	s_mul_i32 s14, s14, s15
	s_ashr_i32 s5, s0, 31
	s_mul_hi_u32 s14, s15, s14
	s_xor_b32 s5, s5, s11
	s_abs_i32 s11, s0
	s_add_i32 s15, s15, s14
	s_mul_hi_u32 s14, s11, s15
	s_mul_i32 s15, s14, s13
	s_sub_i32 s11, s11, s15
	s_add_i32 s15, s14, 1
	s_sub_i32 s16, s11, s13
	s_cmp_ge_u32 s11, s13
	s_cselect_b32 s14, s15, s14
	s_cselect_b32 s11, s16, s11
	s_add_i32 s15, s14, 1
	s_cmp_ge_u32 s11, s13
	s_cselect_b32 s11, s15, s14
	s_xor_b32 s11, s11, s5
	s_sub_i32 s5, s11, s5
	s_lshl_b32 s11, s5, 3
	s_sub_i32 s13, 0xc0, s11
	s_min_i32 s13, s13, 8
	s_abs_i32 s14, s13
	v_cvt_f32_u32_e32 v0, s14
	s_sub_i32 s15, 0, s14
	s_mul_i32 s5, s5, s10
	s_sub_i32 s0, s0, s5
	v_rcp_iflag_f32_e32 v0, v0
	s_abs_i32 s10, s0
	s_xor_b32 s5, s0, s13
	s_ashr_i32 s5, s5, 31
	v_mul_f32_e32 v0, 0x4f7ffffe, v0
	v_cvt_u32_f32_e32 v0, v0
	s_nop 0
	v_readfirstlane_b32 s16, v0
	s_mul_i32 s15, s15, s16
	s_mul_hi_u32 s15, s16, s15
	s_add_i32 s16, s16, s15
	s_mul_hi_u32 s15, s10, s16
	s_mul_i32 s16, s15, s14
	s_sub_i32 s10, s10, s16
	s_add_i32 s16, s15, 1
	s_sub_i32 s17, s10, s14
	s_cmp_ge_u32 s10, s14
	s_cselect_b32 s15, s16, s15
	s_cselect_b32 s10, s17, s10
	s_add_i32 s16, s15, 1
	s_cmp_ge_u32 s10, s14
	s_cselect_b32 s10, s16, s15
	s_xor_b32 s10, s10, s5
	s_sub_i32 s16, s10, s5
	s_mul_i32 s5, s16, s13
	s_sub_i32 s0, s0, s5
	s_add_i32 s0, s0, s11
	s_lshr_b32 s5, s16, 1
	s_cmp_eq_u32 s5, 1
	s_cselect_b32 s10, 10, 0
	s_cmp_eq_u32 s5, 4
	s_cselect_b32 s10, 10, s10
	s_xor_b32 s16, s16, s10

;     DI bool next(int i, Unit& u) const {
;         const long L = (long)i * G + c; if (L >= nwg) return false;
;         int wgid = (int)L; { const int q = nwg / NXCD, r = nwg % NXCD, xcd = wgid % NXCD, off = wgid / NXCD; wgid = (xcd < r ? xcd * (q + 1) : r * (q + 1) + (xcd - r) * q) + off; }
;         const int nig = WGM * nN, gid = wgid / nig, fm = gid * WGM, gsz = (nM - fm) < WGM ? (nM - fm) : WGM;
;         u.pm = fm + ((wgid % nig) % gsz); u.pn = (wgid % nig) / gsz; return true;
;     }
; template <class Epi>
; DI void gemm_phase(LAS unsigned char* lds, const Gemm g, const StaticOrder& S, const Epi& E) {
;     ...
;         const bool has_next = S.next(ui + 1, nxt);
.LBB0_391:
	s_add_i32 s88, s88, 1
	s_mul_i32 s4, s88, s89
	s_mul_hi_u32 s5, s88, s8
	s_add_i32 s5, s5, s4
	s_mul_i32 s4, s88, s8
	s_add_u32 s12, s4, s18
	s_addc_u32 s13, s5, s90
	v_mov_b64_e32 v[0:1], s[46:47]
	v_cmp_ge_i64_e64 s[38:39], s[12:13], v[0:1]
	v_cmp_lt_i64_e64 s[40:41], s[12:13], v[0:1]
	s_and_b64 vcc, exec, s[38:39]
	s_cbranch_vccnz .LBB0_393
	s_ashr_i32 s4, s12, 31
	s_lshr_b32 s4, s4, 29
	s_add_i32 s4, s12, s4
	s_ashr_i32 s5, s4, 3
	s_and_b32 s4, s4, -8
	s_sub_i32 s4, s12, s4
	s_lshr_b32 s12, s4, 31
	s_or_b32 s12, s12, s36
	s_mul_i32 s4, s12, s4
	s_add_i32 s4, s4, s5
	s_abs_i32 s12, s4
	s_mul_hi_u32 s13, s12, s91
	s_mul_i32 s14, s13, s79
	s_ashr_i32 s5, s4, 31
	s_sub_i32 s12, s12, s14
	s_xor_b32 s5, s5, s78
	s_add_i32 s14, s13, 1
	s_sub_i32 s15, s12, s79
	s_cmp_ge_u32 s12, s79
	s_cselect_b32 s13, s14, s13
	s_cselect_b32 s12, s15, s12
	s_add_i32 s14, s13, 1
	s_cmp_ge_u32 s12, s79
	s_cselect_b32 s12, s14, s13
	s_xor_b32 s12, s12, s5
	s_sub_i32 s5, s12, s5
	s_lshl_b32 s12, s5, 3
	s_sub_i32 s13, 0xc0, s12
	s_min_i32 s13, s13, 8
	s_abs_i32 s14, s13
	v_cvt_f32_u32_e32 v0, s14
	s_sub_i32 s17, 0, s14
	s_mul_i32 s5, s5, s71
	s_sub_i32 s4, s4, s5
	v_rcp_iflag_f32_e32 v0, v0
	s_abs_i32 s15, s4
	s_xor_b32 s5, s4, s13
	s_ashr_i32 s5, s5, 31
	v_mul_f32_e32 v0, 0x4f7ffffe, v0
	v_cvt_u32_f32_e32 v0, v0
	s_nop 0
	v_readfirstlane_b32 s33, v0
	s_mul_i32 s17, s17, s33
	s_mul_hi_u32 s17, s33, s17
	s_add_i32 s33, s33, s17
	s_mul_hi_u32 s17, s15, s33
	s_mul_i32 s33, s17, s14
	s_sub_i32 s15, s15, s33
	s_add_i32 s33, s17, 1
	s_sub_i32 s42, s15, s14
	s_cmp_ge_u32 s15, s14
	s_cselect_b32 s17, s33, s17
	s_cselect_b32 s15, s42, s15
	s_add_i32 s33, s17, 1
	s_cmp_ge_u32 s15, s14
	s_cselect_b32 s14, s33, s17
	s_xor_b32 s14, s14, s5
	s_sub_i32 s92, s14, s5
	s_mul_i32 s5, s92, s13
	s_sub_i32 s4, s4, s5
	s_add_i32 s93, s4, s12
	s_lshr_b32 s4, s92, 1
	s_cmp_eq_u32 s4, 1
	s_cselect_b32 s5, 10, 0
	s_cmp_eq_u32 s4, 4
	s_cselect_b32 s5, 10, s5
	s_xor_b32 s92, s92, s5
